# strategy: one static s_setprio 1 for waves 4-7 in the attention phases (B, NSA, dilated)
# speedup vs baseline: 1.0045x; 1.0045x over previous
; __global__ void __launch_bounds__(512, 2) fwd_mega(Params P) {
;     ...
;         if (G > 64) {
;             if (bx < 64) { for (int j = 0; j < 4; ++j) { const int u = bx * 4 + j, qb = u & 63, bh = u >> 6; b_unit(Z, MIX, P.in[12], lds, bh >> 1, bh & 1, qb, gt, wave0); } }
;             else { for (int u = 256 + (bx - 64); u < 2048; u += G - 64) { const int qb = u & 63, bh = u >> 6; b_unit(Z, MIX, P.in[12], lds, bh >> 1, bh & 1, qb, gt, wave0); } }
;         } else { for (int u = bx; u < 2048; u += G) { const int qb = u & 63, bh = u >> 6; b_unit(Z, MIX, P.in[12], lds, bh >> 1, bh & 1, qb, gt, wave0); } }
.LBB0_492:
	s_and_b64 vcc, exec, s[84:85]
	s_cbranch_vccz .Lb_skip_units
	s_cmpk_gt_u32 s89, 0x73f
	s_mov_b32 s3, 0
	s_cbranch_scc1 .LBB0_550
	s_cmp_lt_u32 s93, 0x100
	s_cbranch_scc1 .Lprio_b
	s_setprio 1
.Lprio_b:
	s_mov_b32 s69, 0
	s_mov_b32 s68, s69
	s_mov_b32 s70, s69
	s_mov_b32 s71, s69
	s_mov_b32 s72, s69
	s_mov_b32 s73, s69
	s_mov_b32 s74, s69
	s_mov_b32 s75, s69
	s_mov_b32 s76, s69
	s_mov_b32 s77, s69
	s_mov_b32 s78, s69
	s_mov_b32 s79, s69
	s_mov_b32 s80, s69
	s_mov_b32 s81, s69
	s_mov_b32 s82, s69
	s_mov_b32 s83, s69
	v_mov_b64_e32 v[0:1], s[68:69]
	s_add_i32 s2, s89, -64
	s_sub_i32 s33, s94, 64
	s_movk_i32 s84, 0x1600
	v_mov_b64_e32 v[160:161], s[86:87]
	v_mov_b32_e32 v163, 0
	v_mov_b64_e32 v[2:3], s[70:71]
	v_mov_b64_e32 v[4:5], s[72:73]
	v_mov_b64_e32 v[6:7], s[74:75]
	v_mov_b64_e32 v[8:9], s[76:77]
	v_mov_b64_e32 v[10:11], s[78:79]
	v_mov_b64_e32 v[12:13], s[80:81]
	v_mov_b64_e32 v[14:15], s[82:83]
	s_mov_b32 s76, 0xff800000
	s_mov_b32 s77, 0x40c00000
	v_mov_b32_e32 v170, 0x1600
	v_mov_b32_e32 v171, 0xff800000
	s_mov_b32 s82, 0

; __device__ __forceinline__ bool xb_thread0(int w0) { return w0 == 0 && __builtin_amdgcn_mbcnt_hi(~0u, __builtin_amdgcn_mbcnt_lo(~0u, 0u)) == 0u; }
; #define GRID_BAR() do { XcdBarrier t_ = xbar; asm volatile("" : "+s"(t_.x), "+s"(t_.bar)); xcd_barrier(t_); } while (0)
; __device__ __forceinline__ void xcd_barrier(const XcdBarrier& b) {
;     asm volatile("s_waitcnt vmcnt(0)" ::: "memory");
;     __syncthreads();
;     if (xb_thread0(b.w0)) {
;         unsigned* bar = b.bar;
;         __builtin_amdgcn_s_waitcnt(0);
;         unsigned nloc = b.st[0], nx = b.st[1];
;         if (nloc == 0u) { xcd_barrier_complete(bar, b.x, nloc, nx); b.st[0] = nloc; b.st[1] = nx; }
; __global__ void __launch_bounds__(512, 2) fwd_mega(Params P) {
;     ...
;         __syncthreads();
;     }
;     GRID_BAR();
.LBB0_606:
	s_setprio 0
	v_readlane_b32 s82, v254, 9
	v_readlane_b32 s83, v254, 10
	s_mov_b32 s2, s81
	s_mov_b64 s[0:1], s[82:83]
	s_barrier
	s_waitcnt vmcnt(0)
	v_readlane_b32 s4, v254, 7
	v_readlane_b32 s5, v254, 8
	s_and_b64 vcc, exec, s[4:5]
	s_barrier
	s_cbranch_vccnz .LBB0_652
	v_mbcnt_hi_u32_b32 v0, -1, v204
	v_cmp_eq_u32_e32 vcc, 0, v0
	s_and_saveexec_b64 s[36:37], vcc
	s_cbranch_execz .LBB0_651
	s_add_i32 s4, 0, 0x23840
	v_mov_b32_e32 v0, s4
	s_waitcnt vmcnt(0) expcnt(0) lgkmcnt(0)
	ds_read_b32 v2, v0
	s_add_i32 s4, 0, 0x23844
	v_mov_b32_e32 v0, s4
	ds_read_b32 v0, v0
	s_waitcnt lgkmcnt(1)
	v_cmp_ne_u32_e32 vcc, 0, v2
	s_cbranch_vccnz .LBB0_622
	s_add_u32 s6, s0, 0x1000
	s_addc_u32 s7, s1, 0
	s_add_u32 s8, s0, 0x1100
	s_addc_u32 s9, s1, 0
	s_add_u32 s10, s0, 0x1200
	s_addc_u32 s11, s1, 0
	v_readlane_b32 s4, v254, 0
	s_add_u32 s12, s0, 0x1300
	s_mul_i32 s22, s95, s4
	s_addc_u32 s13, s1, 0
	s_mul_i32 s22, s22, s94
	s_mov_b32 s23, 1
	s_mov_b64 s[4:5], 0
	s_waitcnt lgkmcnt(0)
	v_mov_b64_e32 v[0:1], s[0:1]
	v_mov_b64_e32 v[2:3], s[6:7]
	v_mov_b64_e32 v[4:5], s[8:9]
	v_mov_b64_e32 v[6:7], s[10:11]
	v_mov_b64_e32 v[8:9], s[12:13]
	s_branch .LBB0_612

; __global__ void __launch_bounds__(512, 2) fwd_mega(Params P) {
;     ...
;     {   WS_SETUP();
;         for (int i = 0; i * G + bx < 2048; ++i) { const int u = i * G + bx, j = u >> 5, lvl = j & 7, rnd = j >> 3; const int qb = 63 - (8 * rnd + ((rnd & 1) ? 7 - lvl : lvl)); const int bh = u & 31;
;             nsa_unit(Z, KVC, MIX, lds, bh >> 1, bh & 1, qb, gt, wave0); }
.LBB0_652:
	v_writelane_b32 v254, s89, 12
	v_writelane_b32 v254, s94, 13
	s_mov_b64 s[0:1], s[90:91]
	s_cmpk_gt_i32 s89, 0x7ff
	v_writelane_b32 v254, s95, 14
	v_writelane_b32 v254, s93, 15
	s_waitcnt lgkmcnt(0)
	s_barrier
	s_cbranch_scc1 .LBB0_790
	s_cmp_lt_u32 s93, 0x100
	s_cbranch_scc1 .Lprio_nsa
	s_setprio 1
.Lprio_nsa:
	s_add_u32 s4, s0, 0x4800000
	s_addc_u32 s5, s1, 0
	v_writelane_b32 v254, s4, 16
	s_mov_b32 s73, 0
	s_mov_b32 s72, s73
	v_writelane_b32 v254, s5, 17
	s_add_u32 s4, s0, 0xc800000
	s_addc_u32 s5, s1, 0
	v_writelane_b32 v254, s4, 18
	s_mov_b32 s74, s73
	s_mov_b32 s75, s73
	v_writelane_b32 v254, s5, 19
	s_add_u32 s4, s0, 0xe70200
	s_addc_u32 s5, s1, 0
	v_writelane_b32 v254, s4, 34
	s_add_u32 s0, s0, 0xe00200
	s_addc_u32 s1, s1, 0
	v_writelane_b32 v254, s5, 35
	v_writelane_b32 v254, s0, 36
	s_mov_b32 s76, s73
	s_mov_b32 s77, s73
	v_writelane_b32 v254, s1, 37
	s_add_i32 s0, 0, 0x2000
	v_writelane_b32 v254, s0, 38
	s_add_i32 s0, 0, 0x1800
	v_writelane_b32 v254, s0, 40
	s_add_i32 s0, 0, 0x800
	s_mov_b32 s78, s73
	s_mov_b32 s79, s73
	s_mov_b32 s80, s73
	s_mov_b32 s81, s73
	s_mov_b32 s82, s73
	s_mov_b32 s83, s73
	s_mov_b32 s84, s73
	s_mov_b32 s85, s73
	s_mov_b32 s86, s73
	s_mov_b32 s87, s73
	v_mov_b64_e32 v[0:1], s[72:73]
	s_movk_i32 s88, 0x1000
	v_mov_b32_e32 v161, 0
	v_writelane_b32 v254, s0, 41
	s_mov_b32 s96, 0xff800000
	s_mov_b32 s97, 0x40c00000
	v_mov_b64_e32 v[2:3], s[74:75]
	v_mov_b64_e32 v[4:5], s[76:77]
	v_mov_b64_e32 v[6:7], s[78:79]
	v_mov_b64_e32 v[8:9], s[80:81]
	v_mov_b64_e32 v[10:11], s[82:83]
	v_mov_b64_e32 v[12:13], s[84:85]
	v_mov_b64_e32 v[14:15], s[86:87]
	s_movk_i32 s92, 0x600
	s_movk_i32 s33, 0x900
	v_mov_b32_e32 v168, 0xff800000
	v_mbcnt_hi_u32_b32 v169, -1, v204
	v_mov_b32_e32 v170, 0x7e967699
	v_mov_b32_e32 v171, 0x7f167699
	v_mov_b32_e32 v172, 0x1600
	s_mov_b32 s0, s89
	s_mov_b32 s2, 0
	s_branch .LBB0_655

; __device__ __forceinline__ bool xb_thread0(int w0) { return w0 == 0 && __builtin_amdgcn_mbcnt_hi(~0u, __builtin_amdgcn_mbcnt_lo(~0u, 0u)) == 0u; }
; #define GRID_BAR() do { XcdBarrier t_ = xbar; asm volatile("" : "+s"(t_.x), "+s"(t_.bar)); xcd_barrier(t_); } while (0)
; __device__ __forceinline__ void xcd_barrier(const XcdBarrier& b) {
;     asm volatile("s_waitcnt vmcnt(0)" ::: "memory");
;     __syncthreads();
;     if (xb_thread0(b.w0)) {
;         unsigned* bar = b.bar;
;         __builtin_amdgcn_s_waitcnt(0);
;         unsigned nloc = b.st[0], nx = b.st[1];
;         if (nloc == 0u) { xcd_barrier_complete(bar, b.x, nloc, nx); b.st[0] = nloc; b.st[1] = nx; }
; __global__ void __launch_bounds__(512, 2) fwd_mega(Params P) {
;     ...
;         __syncthreads();
;     }
;     GRID_BAR();
.LBB0_790:
	s_setprio 0
	s_mov_b64 s[0:1], s[82:83]
	s_mov_b32 s2, s81
	s_barrier
	s_waitcnt vmcnt(0)
	v_readlane_b32 s4, v254, 7
	v_readlane_b32 s5, v254, 8
	s_and_b64 vcc, exec, s[4:5]
	s_barrier
	s_cbranch_vccnz .LBB0_836
	v_mbcnt_hi_u32_b32 v0, -1, v204
	v_cmp_eq_u32_e32 vcc, 0, v0
	s_and_saveexec_b64 s[36:37], vcc
	s_cbranch_execz .LBB0_835
	s_add_i32 s4, 0, 0x23840
	v_mov_b32_e32 v0, s4
	s_waitcnt vmcnt(0) expcnt(0) lgkmcnt(0)
	ds_read_b32 v2, v0
	s_add_i32 s4, 0, 0x23844
	v_mov_b32_e32 v0, s4
	ds_read_b32 v0, v0
	s_waitcnt lgkmcnt(1)
	v_cmp_ne_u32_e32 vcc, 0, v2
	s_cbranch_vccnz .LBB0_806
	s_add_u32 s6, s0, 0x1000
	s_addc_u32 s7, s1, 0
	s_add_u32 s8, s0, 0x1100
	s_addc_u32 s9, s1, 0
	s_add_u32 s10, s0, 0x1200
	s_addc_u32 s11, s1, 0
	v_readlane_b32 s4, v254, 0
	s_add_u32 s12, s0, 0x1300
	s_mul_i32 s22, s95, s4
	s_addc_u32 s13, s1, 0
	s_mul_i32 s22, s22, s94
	s_mov_b32 s23, 1
	s_mov_b64 s[4:5], 0
	s_waitcnt lgkmcnt(0)
	v_mov_b64_e32 v[0:1], s[0:1]
	v_mov_b64_e32 v[2:3], s[6:7]
	v_mov_b64_e32 v[4:5], s[8:9]
	v_mov_b64_e32 v[6:7], s[10:11]
	v_mov_b64_e32 v[8:9], s[12:13]
	s_branch .LBB0_796

; #define LAS __attribute__((address_space(3)))
; #define C_LOADP(p_) do { const bf16_t* q_ = (p_); rka = ldg16(q_ + kvlane); rva = ldg16(q_ + (size_t)16 * T * 64 + kvlane); rkb = ldg16(q_ + (size_t)T * 64 + kvlane); rvb = ldg16(q_ + (size_t)17 * T * 64 + kvlane); } while (0)
; __device__ __forceinline__ void c_phase(const bf16_t* Z, bf16_t* MIX, float* LSE, ldsp lds, int pi, int bx, int G, unsigned& gt, int wave0, int ucount) {
;     int tid_; asm volatile("v_mbcnt_lo_u32_b32 %0, -1, 0\n\tv_mbcnt_hi_u32_b32 %0, -1, %0" : "=&v"(tid_)); tid_ += wave0 * 64; const int tid = tid_, lane = tid & 63, w = __builtin_amdgcn_readfirstlane(tid >> 6), r32 = lane & 31, hi = lane >> 5;
;     const int hsel = w >> 2, gq = (w < 4) ? w : 7 - w, key = tid >> 3, ch = tid & 7;
;     const int ldil = 2 * pi, dil = 1 << ldil, lnb = 5 - ldil;
;     LAS float* wsf = (LAS float*)(lds + LDS_WSF) + w * 64;
;     const size_t tstride = (size_t)64 * dil * 64;
;     const unsigned kvlane = (unsigned)(key * dil * 64 + ch * 8), qlane = (unsigned)(r32 * dil * 64), olane = (unsigned)((lane >> 3) * dil * 1024 + (lane & 7) * 8), llane = (unsigned)(r32 * dil * 16);
;     ...
;     const u32x4 z4 = {0u, 0u, 0u, 0u};
;     u32x4 rka = z4, rva = z4, rkb = z4, rvb = z4;
;     const int per = (ucount + G - 1) / G, uend = (bx + 1) * per < ucount ? (bx + 1) * per : ucount;
;     int u = bx * per;
;     if (u >= uend) return;
;     {   C_DEC(u, b, hp, rs, blk); const int kt0 = blk >= 1 ? 2 * blk - 2 : 0; const bf16_t* kvp = C_KVP(b, hp, rs);
;         C_LOADP(kvp + kt0 * tstride);
;         { const ldsp b0 = lds + (gt & 1u) * 32768; tile_store(b0, rka, rva, key, ch); tile_store(b0 + 16384, rkb, rvb, key, ch); }
;         C_LOADP(kvp + (kt0 + 1) * tstride);
.LBB0_1032:
	s_mov_b64 s[0:1], s[90:91]
	v_mbcnt_lo_u32_b32 v18, -1, 0
	v_mbcnt_hi_u32_b32 v18, -1, v18
	s_cmp_lt_u32 s93, 0x100
	s_cbranch_scc1 .Lprio_c
	s_setprio 1
.Lprio_c:
	s_andn2_b64 vcc, exec, s[66:67]
	v_add_u32_e32 v19, s93, v18
	s_nop 0
	v_readfirstlane_b32 s2, v19
	s_cbranch_vccnz .LBB0_1096
	s_add_u32 s4, s0, 0x200000
	s_addc_u32 s29, s1, 0
	s_add_u32 s5, s0, 0x4800000
	v_writelane_b32 v255, s5, 18
	s_addc_u32 s5, s1, 0
	s_add_u32 s80, s0, 0xc800000
	s_addc_u32 s81, s1, 0
	s_and_b32 s0, s2, 0x3fffffc0
	s_lshl_b32 s0, s0, 2
	v_writelane_b32 v255, s5, 19
	s_lshl_b32 s31, s38, 1
	s_add_i32 s5, s0, 0
	s_ashr_i32 s8, s2, 6
	s_ashr_i32 s30, s2, 8
	s_sub_i32 s33, 5, s31
	s_add_i32 s5, s5, 0x23000
	s_sub_i32 s0, 7, s8
	s_cmp_lt_i32 s8, 4
	s_cselect_b32 s2, s8, s0
	s_lshl_b32 s0, -1, s33
	v_readlane_b32 s28, v255, 6
	s_not_b32 s34, s0
	s_andn2_b32 s0, s28, s0
	s_ashr_i32 s1, s28, s33
	s_lshl_b32 s6, -1, s31
	v_readlane_b32 s12, v254, 18
	s_andn2_b32 s12, s1, s6
	s_lshl_b32 s1, s0, 1
	s_not_b32 s35, s6
	s_add_i32 s1, s1, -2
	s_cmp_lg_u32 s0, 0
	v_readlane_b32 s6, v255, 7
	v_readlane_b32 s13, v254, 19
	s_cselect_b32 s0, s1, 0
	v_readlane_b32 s7, v255, 8
	s_add_u32 s1, s80, s6
	s_addc_u32 s6, s81, s7
	s_lshl_b64 s[10:11], s[12:13], 7
	s_add_u32 s7, s1, s10
	s_addc_u32 s6, s6, s11
	s_mov_b32 s1, s13
	s_add_i32 s72, s31, 12
	v_ashrrev_i32_e32 v19, 3, v19
	v_and_b32_e32 v44, 7, v18
	s_lshl_b64 s[10:11], s[0:1], s72
	v_lshlrev_b32_e32 v20, s31, v19
	v_lshlrev_b32_e32 v21, 3, v44
	s_lshl_b64 s[10:11], s[10:11], 1
	v_lshl_or_b32 v184, v20, 6, v21
	s_add_u32 s10, s7, s10
	v_mov_b32_e32 v185, v177
	s_addc_u32 s11, s6, s11
	v_lshlrev_b64 v[36:37], 1, v[184:185]
	v_lshl_add_u64 v[32:33], s[10:11], 0, v[36:37]
	global_load_dwordx4 v[20:23], v[32:33], off
	s_mov_b32 s9, 0x800000
	v_add_co_u32_e32 v24, vcc, s9, v32
	s_mov_b32 s10, 0x80000
	s_nop 0
	v_addc_co_u32_e32 v25, vcc, 0, v33, vcc
	v_add_co_u32_e32 v28, vcc, s10, v32
	s_mov_b32 s11, 0x880000
	s_nop 0
	v_addc_co_u32_e32 v29, vcc, 0, v33, vcc
	global_load_dwordx4 v[24:27], v[24:25], off
	v_add_co_u32_e32 v32, vcc, s11, v32
	global_load_dwordx4 v[28:31], v[28:29], off
	s_nop 0
	v_addc_co_u32_e32 v33, vcc, 0, v33, vcc
	global_load_dwordx4 v[32:35], v[32:33], off
	s_lshl_b32 s1, s3, 15
	s_and_b32 s1, s1, 0x8000
	v_lshlrev_b32_e32 v202, 10, v44
	v_lshlrev_b32_e32 v44, 5, v44
	v_lshlrev_b32_e32 v45, 4, v19
	s_add_i32 s1, s1, 0
	v_xor_b32_e32 v203, v45, v44
	v_lshlrev_b32_e32 v19, 6, v19
	v_add3_u32 v44, s1, v202, v203
	v_and_b32_e32 v204, 0x1000, v202
	v_and_b32_e32 v205, 0xfffffc00, v19
	v_readlane_b32 s14, v254, 20
	v_readlane_b32 s15, v254, 21
	s_or_b32 s12, s0, 1
	v_readlane_b32 s16, v254, 22
	v_readlane_b32 s17, v254, 23
	v_readlane_b32 s18, v254, 24
	v_readlane_b32 s19, v254, 25
	v_readlane_b32 s20, v254, 26
	v_readlane_b32 s21, v254, 27
	v_readlane_b32 s22, v254, 28
	v_readlane_b32 s23, v254, 29
	v_readlane_b32 s24, v254, 30
	v_readlane_b32 s25, v254, 31
	v_readlane_b32 s26, v254, 32
	v_readlane_b32 s27, v254, 33
	v_and_b32_e32 v206, 0x3c0, v19
	v_lshlrev_b32_e32 v19, 4, v18
	v_and_b32_e32 v207, 48, v19
	v_and_b32_e32 v17, 31, v18
	v_and_b32_e32 v38, 63, v18
	v_lshlrev_b32_e32 v40, s31, v17
	v_bfe_u32 v43, v18, 5, 1
	v_lshlrev_b32_e32 v176, 7, v40
	v_writelane_b32 v255, s38, 20
	v_lshlrev_b32_e32 v186, 4, v43
	v_mov_b32_e32 v187, v177
	v_lshlrev_b32_e32 v41, 3, v18
	v_bfe_u32 v39, v18, 3, 3
	v_and_b32_e32 v42, 56, v41
	v_and_b32_e32 v250, 0xc0, v19
	v_lshlrev_b32_e32 v209, 2, v43
	v_lshlrev_b32_e32 v16, s31, v39
	v_or_b32_e32 v211, 1, v209
	v_lshl_or_b32 v16, v16, 10, v42
	v_lshlrev_b32_e32 v182, 4, v40
	v_mov_b32_e32 v183, v177
	v_or_b32_e32 v210, 32, v209
	v_or_b32_e32 v217, 33, v209
	v_or_b32_e32 v218, 2, v209
	v_or_b32_e32 v219, 34, v209
	v_or_b32_e32 v220, 3, v209
	v_or_b32_e32 v221, 35, v209
	v_or_b32_e32 v222, 8, v209
	v_or_b32_e32 v223, 40, v209
	v_or_b32_e32 v224, 9, v209
	v_or_b32_e32 v225, 41, v209
	v_or_b32_e32 v226, 10, v209
	v_or_b32_e32 v227, 42, v209
	v_or_b32_e32 v228, 11, v209
	v_or_b32_e32 v229, 43, v209
	s_waitcnt vmcnt(0)
; #define C_LOADP(p_) do { const bf16_t* q_ = (p_); rka = ldg16(q_ + kvlane); rva = ldg16(q_ + (size_t)16 * T * 64 + kvlane); rkb = ldg16(q_ + (size_t)T * 64 + kvlane); rvb = ldg16(q_ + (size_t)17 * T * 64 + kvlane); } while (0)
; __device__ __forceinline__ void c_phase(const bf16_t* Z, bf16_t* MIX, float* LSE, ldsp lds, int pi, int bx, int G, unsigned& gt, int wave0, int ucount) {
;     ...
;     {   C_DEC(u, b, hp, rs, blk); const int kt0 = blk >= 1 ? 2 * blk - 2 : 0; const bf16_t* kvp = C_KVP(b, hp, rs);
;         C_LOADP(kvp + kt0 * tstride);
;         { const ldsp b0 = lds + (gt & 1u) * 32768; tile_store(b0, rka, rva, key, ch); tile_store(b0 + 16384, rkb, rvb, key, ch); }
;         C_LOADP(kvp + (kt0 + 1) * tstride);
;         __syncthreads(); }
	ds_write_b128 v44, v[20:23]
	v_add3_u32 v20, s1, v204, v205
	s_mov_b32 s1, s13
	v_writelane_b32 v254, s0, 18
	v_add3_u32 v20, v20, v206, v207
	ds_write_b128 v20, v[24:27] offset:8192
	ds_write_b128 v44, v[28:31] offset:16384
	ds_write_b128 v20, v[32:35] offset:24576
	v_writelane_b32 v254, s1, 19
	v_writelane_b32 v254, s2, 20
	v_writelane_b32 v254, s3, 21
	v_writelane_b32 v254, s4, 22
	v_writelane_b32 v254, s5, 23
	v_writelane_b32 v254, s6, 24
	v_writelane_b32 v254, s7, 25
	v_writelane_b32 v254, s8, 26
	v_writelane_b32 v254, s9, 27
	v_writelane_b32 v254, s10, 28
	v_writelane_b32 v254, s11, 29
	v_writelane_b32 v254, s12, 30
	v_writelane_b32 v254, s13, 31
	v_writelane_b32 v254, s14, 32
	v_writelane_b32 v254, s15, 33
	s_lshl_b64 s[0:1], s[12:13], s72
	s_lshl_b64 s[0:1], s[0:1], 1
	s_add_u32 s0, s7, s0
	s_addc_u32 s1, s6, s1
	v_lshl_add_u64 v[20:21], s[0:1], 0, v[36:37]
	v_add_co_u32_e32 v22, vcc, s9, v20
	global_load_dwordx4 v[128:131], v[20:21], off
	s_nop 0
	v_addc_co_u32_e32 v23, vcc, 0, v21, vcc
	global_load_dwordx4 v[132:135], v[22:23], off
	v_add_co_u32_e32 v22, vcc, s10, v20
	s_lshl_b32 s10, s2, 5
	s_nop 0
	v_addc_co_u32_e32 v23, vcc, 0, v21, vcc
	v_add_co_u32_e32 v20, vcc, s11, v20
	global_load_dwordx4 v[136:139], v[22:23], off
	s_nop 0
	v_addc_co_u32_e32 v21, vcc, 0, v21, vcc
	global_load_dwordx4 v[140:143], v[20:21], off
	s_cmp_lg_u32 s38, 0
	s_cselect_b64 s[82:83], -1, 0
	s_cmp_eq_u32 s38, 0
	s_cselect_b64 s[0:1], -1, 0
	v_writelane_b32 v254, s0, 36
	s_add_i32 s9, s31, 13
	s_lshl_b32 s2, 0x2000, s31
	v_writelane_b32 v254, s1, 37
	s_lshl_b32 s0, s30, 14
	s_add_i32 s94, s0, 0
	s_cmp_eq_u32 s38, 1
	v_cmp_gt_u32_e64 s[6:7], 32, v38
	s_cselect_b64 s[0:1], -1, 0
	s_and_b64 s[0:1], s[0:1], s[6:7]
	v_lshl_add_u64 v[20:21], s[80:81], 0, v[176:177]
	v_writelane_b32 v255, s0, 21
	s_mulk_i32 s8, 0x2200
	v_lshl_add_u64 v[188:189], v[20:21], 0, v[186:187]
	v_lshlrev_b32_e32 v20, 4, v17
	v_writelane_b32 v255, s1, 22
	s_add_i32 s0, s8, 0
	v_bitop3_b32 v208, v20, v18, 32 bitop3:0x78
	v_lshlrev_b32_e32 v20, 2, v17
	v_lshlrev_b32_e32 v18, 1, v18
	s_add_i32 s0, s0, 0x10000
	v_and_b32_e32 v247, 32, v18
	v_add_u32_e32 v18, s0, v20
	v_lshl_add_u32 v19, v42, 2, s0
	s_lshl_b64 s[0:1], 1, s9
	v_writelane_b32 v255, s0, 23
	v_writelane_b32 v254, s30, 16
	v_add_u32_e32 v246, s5, v20
	v_writelane_b32 v255, s1, 24
	s_lshl_b64 s[0:1], 2, s9
	v_writelane_b32 v255, s0, 25
	v_mul_u32_u24_e32 v20, 0x440, v43
	v_mul_u32_u24_e32 v21, 0x110, v211
	v_writelane_b32 v255, s1, 26
	s_lshl_b64 s[0:1], 3, s9
	v_writelane_b32 v255, s0, 27
	v_mul_u32_u24_e32 v22, 0x110, v39
	v_lshlrev_b32_e32 v187, 10, v43
	v_writelane_b32 v255, s1, 28
	s_lshl_b64 s[0:1], 0x2000, s31
	v_writelane_b32 v254, s0, 38
	v_writelane_b32 v255, s29, 29
	v_writelane_b32 v255, s4, 30
	v_writelane_b32 v254, s1, 39
	s_lshl_b64 s[0:1], 0x4000, s31
	v_writelane_b32 v254, s0, 34
	v_writelane_b32 v255, s33, 31
	v_or_b32_e32 v230, 16, v209
	v_writelane_b32 v254, s1, 35
	v_writelane_b32 v254, s31, 40
	s_lshl_b64 s[0:1], 0x6000, s31
	v_writelane_b32 v254, s0, 0
	v_or_b32_e32 v231, 48, v209
	v_or_b32_e32 v232, 17, v209
	v_writelane_b32 v254, s1, 1
	s_add_i32 s0, s10, 0xffffff80
	v_or_b32_e32 v233, 49, v209
	v_or_b32_e32 v234, 18, v209
	v_or_b32_e32 v235, 50, v209
	v_or_b32_e32 v236, 19, v209
	v_or_b32_e32 v237, 51, v209
	v_or_b32_e32 v238, 24, v209
	v_or_b32_e32 v239, 56, v209
	v_or_b32_e32 v240, 25, v209
	v_or_b32_e32 v241, 57, v209
	v_or_b32_e32 v242, 26, v209
	v_or_b32_e32 v243, 58, v209
	v_or_b32_e32 v244, 27, v209
	v_or_b32_e32 v245, 59, v209
	v_and_b32_e32 v248, 24, v41
	v_lshlrev_b32_e32 v249, 8, v43
	v_lshl_add_u32 v251, v39, 2, s5
	v_writelane_b32 v254, s10, 41
	v_or_b32_e32 v252, s0, v17
	v_sub_u32_e32 v253, 0, v209
	v_lshlrev_b32_e32 v190, 1, v16
	v_add_u32_e32 v215, v18, v20
	v_add_u32_e32 v178, v18, v21
	v_add_u32_e32 v179, v19, v22
	s_mov_b32 s1, s28
	v_writelane_b32 v255, s35, 32
	s_waitcnt lgkmcnt(0)
	s_mov_b32 s101, 0
	s_barrier

; #define PG8_STAGE(bufoff, gbase, voff) do { _Pragma("unroll") for (int _i = 0; _i < 2; ++_i) \
;         __builtin_amdgcn_global_load_lds((const unsigned*)((const char*)(gbase) + (voff)[_i]), (PG8_LAS unsigned*)(lds + (bufoff) + ldsw + _i * 8192), 16, 0, 0); } while (0)
; #define PG8_WAIT_V(n) asm volatile("s_waitcnt vmcnt(" #n ")" ::: "memory")
; #define PG8_BAR __builtin_amdgcn_s_barrier()
; template <class Epi, class Sched, bool ALIGN_EPI = false, bool SP2 = false>
; __device__ __forceinline__ void gemm_phase(PG8_LAS unsigned char* lds, const Gemm g, const Sched& S, const Epi& E, int wave0) {
;     int tid_; asm volatile("v_mbcnt_lo_u32_b32 %0, -1, 0\n\tv_mbcnt_hi_u32_b32 %0, -1, %0" : "=&v"(tid_)); tid_ += wave0 * 64; const int tid = tid_, wid = __builtin_amdgcn_readfirstlane(tid >> 6), lane = tid & 63, wr = wid >> 2, wc = wid & 3, fr = lane & 15, fq = lane >> 4;
;     const int K = g.K, nt = K / BK;
;     unsigned voffA[2], voffB[2];
; #pragma unroll
;     for (int i = 0; i < 2; ++i) { int R, C; stage_rc(tid * 16 + i * 8192, R, C); const int Rb = Epi::PERM ? ((R & ~31) + perm32(R & 31)) : R;
;         voffA[i] = (unsigned)(R * g.lda + C) * 2u; voffB[i] = (unsigned)(Rb * K + C) * 2u; }
;     const size_t kstep = (size_t)(BK * 2); const size_t kstepA = (size_t)g.kstepA; const size_t hstepA = (size_t)HALF * g.lda * 2;
;     const size_t hstep = (size_t)HALF * K * 2;
;     const size_t tstep = 2 * hstep;
;     const unsigned ldsw = (unsigned)wid * 1024u;
;     const int aoff = lds_byte(wr * 64 + fr, fq * 8), boff = lds_byte(wc * 32 + fr, fq * 8);
;     ...
;     const char* cA = a_base(g, cur); const char* cB = (const char*)g.Bt + (size_t)cur.pn * tstep;
;     S.a_ready(cur);
;     if constexpr (SP2) {
;         PG8_STAGE(PG8_SB(0, 0), cB, voffB); PG8_STAGE(PG8_SB(0, 1), cB + hstep, voffB); PG8_STAGE(PG8_SA(0, 0), cA, voffA); PG8_STAGE(PG8_SA(0, 1), cA + hstepA, voffA);
;         if (wr == 1) PG8_BAR;
;         PG8_WAIT_V(2); PG8_BAR;
;         PG8_STAGE(PG8_SB(1, 0), cB + kstep, voffB); PG8_STAGE(PG8_SA(1, 0), cA + kstepA, voffA); PG8_STAGE(PG8_SB(1, 1), cB + hstep + kstep, voffB);
;         PG8_WAIT_V(6); PG8_BAR;
.LBB0_1140:
	s_setprio 0
	s_mov_b64 s[0:1], s[90:91]
	v_readlane_b32 s4, v254, 42
	v_mbcnt_lo_u32_b32 v30, -1, 0
	v_mbcnt_hi_u32_b32 v30, -1, v30
	v_readlane_b32 s5, v254, 43
	v_add_u32_e32 v16, s93, v30
	s_and_b64 vcc, exec, s[4:5]
	v_readfirstlane_b32 s4, v16
	s_cbranch_vccnz .LBB0_1176
	v_lshlrev_b32_e32 v17, 4, v16
	v_add_u32_e32 v18, 0x2000, v17
	v_ashrrev_i32_e32 v19, 31, v18
	v_lshrrev_b32_e32 v19, 22, v19
	v_add_u32_e32 v19, v18, v19
	v_ashrrev_i32_e32 v24, 10, v19
	v_mul_i32_i24_e32 v19, 0x400, v24
	v_sub_u32_e32 v18, v18, v19
	v_lshrrev_b32_e32 v19, 4, v18
	v_bitop3_b32 v18, v19, v18, 32 bitop3:0x6c
	v_ashrrev_i32_e32 v19, 31, v18
	v_lshrrev_b32_e32 v19, 26, v19
	v_add_u32_e32 v19, v18, v19
	v_lshlrev_b32_e32 v20, 3, v24
	v_ashrrev_i32_e32 v25, 6, v19
	v_and_b32_e32 v20, -16, v20
	v_add_u32_e32 v20, v25, v20
	v_and_b32_e32 v21, 3, v25
	s_mov_b32 s7, 0x1fffe0
	v_lshrrev_b32_e32 v22, 2, v20
	v_lshlrev_b32_e32 v23, 1, v20
	v_and_or_b32 v21, v20, s7, v21
	v_and_b32_e32 v22, 4, v22
	v_and_b32_e32 v23, 24, v23
	v_and_b32_e32 v19, 0xc0, v19
	v_or3_b32 v21, v21, v22, v23
	v_sub_u32_e32 v18, v18, v19
	v_mov_b32_e32 v23, 1
	v_lshlrev_b32_e32 v22, 5, v24
	v_ashrrev_i16_sdwa v18, v23, sext(v18) dst_sel:DWORD dst_unused:UNUSED_PAD src0_sel:DWORD src1_sel:BYTE_0
	v_and_b32_e32 v22, 32, v22
	v_bfe_i32 v26, v18, 0, 16
	v_add_lshl_u32 v18, v22, v26, 1
	s_waitcnt vmcnt(0)
	v_lshl_add_u32 v172, v21, 11, v18
	v_lshl_add_u32 v174, v20, 11, v18
	v_bfe_i32 v18, v16, 27, 1
	v_lshrrev_b32_e32 v18, 22, v18
	v_add_u32_e32 v18, v17, v18
	v_and_b32_e32 v18, 0xfffffc00, v18
	v_sub_u32_e32 v17, v17, v18
	v_lshrrev_b32_e32 v18, 4, v17
	v_ashrrev_i32_e32 v19, 31, v16
	v_bitop3_b32 v17, v18, v17, 32 bitop3:0x6c
	v_lshrrev_b32_e32 v19, 26, v19
	v_ashrrev_i32_e32 v18, 31, v17
	v_add_u32_e32 v16, v16, v19
	v_lshrrev_b32_e32 v18, 26, v18
	v_ashrrev_i32_e32 v28, 6, v16
	v_add_u32_e32 v18, v17, v18
	v_lshlrev_b32_e32 v16, 3, v28
	s_add_u32 s2, s0, 0x4800000
	v_ashrrev_i32_e32 v27, 6, v18
	v_and_b32_e32 v16, -16, v16
	s_addc_u32 s28, s1, 0
	v_add_u32_e32 v16, v27, v16
	s_add_u32 s29, s0, 0x2280000
	v_and_b32_e32 v19, 3, v27
	v_lshrrev_b32_e32 v20, 2, v16
	v_lshlrev_b32_e32 v21, 1, v16
	v_and_b32_e32 v18, 0xc0, v18
	s_addc_u32 s30, s1, 0
	s_ashr_i32 s6, s4, 6
	v_and_or_b32 v19, v16, s7, v19
	v_and_b32_e32 v20, 4, v20
	v_and_b32_e32 v21, 24, v21
	v_sub_u32_e32 v17, v17, v18
	s_ashr_i32 s5, s4, 8
	s_lshl_b32 s31, s6, 10
	v_or3_b32 v19, v19, v20, v21
	v_lshlrev_b32_e32 v20, 5, v28
	v_ashrrev_i16_sdwa v17, v23, sext(v17) dst_sel:DWORD dst_unused:UNUSED_PAD src0_sel:DWORD src1_sel:BYTE_0
	v_readlane_b32 s8, v255, 4
	v_and_b32_e32 v20, 32, v20
	v_bfe_i32 v29, v17, 0, 16
	v_readlane_b32 s9, v255, 5
	s_add_u32 s22, s29, s8
	v_add_lshl_u32 v17, v20, v29, 1
	s_addc_u32 s23, s30, s9
	s_add_i32 s33, s31, 0
	v_lshl_add_u32 v176, v19, 11, v17
	s_add_i32 m0, s33, 0x10000
	v_readlane_b32 s8, v255, 2
	global_load_lds_dwordx4 v176, s[22:23]
	s_add_i32 m0, s33, 0x12000
	v_readlane_b32 s9, v255, 3
	s_add_u32 s24, s2, s8
	s_addc_u32 s25, s28, s9
	s_add_u32 s8, s22, 0x40000
	global_load_lds_dwordx4 v172, s[22:23]
	s_addc_u32 s9, s23, 0
	s_add_i32 m0, s33, 0x14000
	s_add_i32 s34, s33, 0x2000
	global_load_lds_dwordx4 v176, s[8:9]
	s_add_i32 m0, s33, 0x16000
	v_lshl_add_u32 v182, v16, 11, v17
	global_load_lds_dwordx4 v172, s[8:9]
	s_mov_b32 m0, s33
	s_add_u32 s8, s24, 0x40000
	global_load_lds_dwordx4 v182, s[24:25]
	s_mov_b32 m0, s34
	s_addc_u32 s9, s25, 0
	s_add_i32 s35, s33, 0x4000
	global_load_lds_dwordx4 v174, s[24:25]
	s_mov_b32 m0, s35
	s_add_i32 s36, s33, 0x6000
	global_load_lds_dwordx4 v182, s[8:9]
	s_mov_b32 m0, s36
	v_mov_b32_e32 v173, v177
	global_load_lds_dwordx4 v174, s[8:9]
	v_mov_b32_e32 v183, v177
	v_mov_b32_e32 v175, v177
	s_cmp_eq_u32 s5, 1
	v_lshl_add_u64 v[22:23], s[22:23], 0, v[176:177]
	v_lshl_add_u64 v[20:21], s[22:23], 0, v[172:173]
	v_lshl_add_u64 v[16:17], s[24:25], 0, v[182:183]
	s_cselect_b64 s[10:11], -1, 0
	s_cmp_lg_u32 s5, 1
	v_lshl_add_u64 v[18:19], s[24:25], 0, v[174:175]
	s_cbranch_scc1 .LBB0_1143
	s_barrier
